# GEMM unit set-up: accumulator zeroing with v_mov_b64 (63 instead of 126 moves)
# speedup vs baseline: 1.0318x; 1.0033x over previous
.LBB0_245:
	s_add_u32 s6, s90, 0x80
	s_addc_u32 s7, s91, 0
	s_add_u32 s8, s42, 0x100
	v_mov_b32_e32 v0, 0
	s_addc_u32 s66, s43, 0
	s_mov_b32 s42, 0
	v_mov_b32_e32 v1, v0
	v_mov_b64_e32 v[2:3], v[0:1]
	v_mov_b64_e32 v[4:5], v[0:1]
	v_mov_b64_e32 v[6:7], v[0:1]
	v_mov_b64_e32 v[8:9], v[0:1]
	v_mov_b64_e32 v[10:11], v[0:1]
	v_mov_b64_e32 v[12:13], v[0:1]
	v_mov_b64_e32 v[14:15], v[0:1]
	v_mov_b64_e32 v[16:17], v[0:1]
	v_mov_b64_e32 v[18:19], v[0:1]
	v_mov_b64_e32 v[20:21], v[0:1]
	v_mov_b64_e32 v[22:23], v[0:1]
	v_mov_b64_e32 v[24:25], v[0:1]
	v_mov_b64_e32 v[26:27], v[0:1]
	v_mov_b64_e32 v[28:29], v[0:1]
	v_mov_b64_e32 v[30:31], v[0:1]
	v_mov_b64_e32 v[32:33], v[0:1]
	v_mov_b64_e32 v[34:35], v[0:1]
	v_mov_b64_e32 v[36:37], v[0:1]
	v_mov_b64_e32 v[38:39], v[0:1]
	v_mov_b64_e32 v[40:41], v[0:1]
	v_mov_b64_e32 v[42:43], v[0:1]
	v_mov_b64_e32 v[44:45], v[0:1]
	v_mov_b64_e32 v[46:47], v[0:1]
	v_mov_b64_e32 v[48:49], v[0:1]
	v_mov_b64_e32 v[50:51], v[0:1]
	v_mov_b64_e32 v[52:53], v[0:1]
	v_mov_b64_e32 v[54:55], v[0:1]
	v_mov_b64_e32 v[56:57], v[0:1]
	v_mov_b64_e32 v[58:59], v[0:1]
	v_mov_b64_e32 v[60:61], v[0:1]
	v_mov_b64_e32 v[62:63], v[0:1]
	v_mov_b64_e32 v[64:65], v[0:1]
	v_mov_b64_e32 v[66:67], v[0:1]
	v_mov_b64_e32 v[68:69], v[0:1]
	v_mov_b64_e32 v[70:71], v[0:1]
	v_mov_b64_e32 v[72:73], v[0:1]
	v_mov_b64_e32 v[74:75], v[0:1]
	v_mov_b64_e32 v[76:77], v[0:1]
	v_mov_b64_e32 v[78:79], v[0:1]
	v_mov_b64_e32 v[80:81], v[0:1]
	v_mov_b64_e32 v[82:83], v[0:1]
	v_mov_b64_e32 v[84:85], v[0:1]
	v_mov_b64_e32 v[86:87], v[0:1]
	v_mov_b64_e32 v[88:89], v[0:1]
	v_mov_b64_e32 v[90:91], v[0:1]
	v_mov_b64_e32 v[92:93], v[0:1]
	v_mov_b64_e32 v[94:95], v[0:1]
	v_mov_b64_e32 v[96:97], v[0:1]
	v_mov_b64_e32 v[98:99], v[0:1]
	v_mov_b64_e32 v[100:101], v[0:1]
	v_mov_b64_e32 v[102:103], v[0:1]
	v_mov_b64_e32 v[104:105], v[0:1]
	v_mov_b64_e32 v[106:107], v[0:1]
	v_mov_b64_e32 v[108:109], v[0:1]
	v_mov_b64_e32 v[110:111], v[0:1]
	v_mov_b64_e32 v[112:113], v[0:1]
	v_mov_b64_e32 v[114:115], v[0:1]
	v_mov_b64_e32 v[116:117], v[0:1]
	v_mov_b64_e32 v[118:119], v[0:1]
	v_mov_b64_e32 v[120:121], v[0:1]
	v_mov_b64_e32 v[122:123], v[0:1]
	v_mov_b64_e32 v[124:125], v[0:1]
	v_mov_b64_e32 v[126:127], v[0:1]
	s_waitcnt lgkmcnt(0)
	v_add_u32_e32 v222, 0x10000, v157
